# v2 plus mixer queue order: prep1 tail interleaved with select units
# speedup vs baseline: 1.0766x; 1.0023x over previous
.LBB0_691:
	s_or_b64 exec, exec, s[4:5]
	s_waitcnt lgkmcnt(0)
	s_barrier
	s_waitcnt vmcnt(0)
	ds_read_b32 v2, v207
	s_movk_i32 s0, 0xdff
	s_mov_b64 s[4:5], -1
	s_waitcnt lgkmcnt(0)
	s_barrier
	v_cmp_lt_i32_e32 vcc, s0, v2
	v_readfirstlane_b32 s58, v2
	s_cbranch_vccnz .LBB0_686
	s_cmpk_lt_u32 s58, 576
	s_cbranch_scc1 .Lq0_done
	s_cmpk_ge_u32 s58, 1344
	s_cbranch_scc1 .Lq0_done
	s_sub_u32 s0, s58, 576
	s_mul_hi_u32 s29, s0, 0xaaaaaaab
	s_lshr_b32 s29, s29, 1
	s_mul_i32 vcc_lo, s29, 3
	s_sub_u32 s0, s0, vcc_lo
	s_cmp_eq_u32 s0, 0
	s_cbranch_scc1 .Lq0_r1s
	s_lshl_b32 s29, s29, 1
	s_add_u32 s58, s29, s0
	s_addk_i32 s58, 575
	s_branch .Lq0_done
.Lq0_r1s:
	s_add_u32 s58, s29, 1088
.Lq0_done:
	s_cmpk_lt_i32 s58, 0x100
	s_cbranch_scc1 .LBB0_702
	s_cmpk_gt_u32 s58, 0x13f
	s_cbranch_scc0 .LBB0_699
	s_cmpk_gt_u32 s58, 0x43f
	s_cbranch_scc0 .LBB0_696
	s_add_i32 s29, s58, 0xfffffc00
	s_mov_b64 s[4:5], 0
